# v17 + mixpre conv: next-iteration column lines touched by dword loads after the second buffer's loads (L2 warm-up), counted waits leave them outstanding, skip paths drain
# speedup vs baseline: 1.0055x; 1.0055x over previous
.LBB0_622:
	s_andn2_b64 vcc, exec, s[4:5]
	s_cbranch_vccnz .LBB0_657
	s_lshl_b32 s0, s75, 3
	s_abs_i32 s1, s0
	s_waitcnt vmcnt(0)
	v_cvt_f32_u32_e32 v4, s1
	s_sub_i32 s4, 0, s1
	s_add_i32 s2, s0, 0x87ff
	s_xor_b32 s0, s2, s0
	v_rcp_iflag_f32_e32 v4, v4
	s_abs_i32 s2, s2
	s_ashr_i32 s0, s0, 31
	v_ashrrev_i32_e32 v5, 6, v186
	v_mul_f32_e32 v4, 0x4f7ffffe, v4
	v_cvt_u32_f32_e32 v4, v4
	v_lshl_add_u32 v5, s64, 3, v5
	v_mov_b32_e32 v252, 0x500
	v_mov_b32_e32 v250, 0x3c0
	v_readfirstlane_b32 s5, v4
	s_mul_i32 s4, s4, s5
	s_mul_hi_u32 s4, s5, s4
	s_add_i32 s5, s5, s4
	s_mul_hi_u32 s4, s2, s5
	s_mul_i32 s5, s4, s1
	s_sub_i32 s2, s2, s5
	s_add_i32 s6, s4, 1
	s_sub_i32 s5, s2, s1
	s_cmp_ge_u32 s2, s1
	s_cselect_b32 s4, s6, s4
	s_cselect_b32 s2, s5, s2
	s_add_i32 s5, s4, 1
	s_cmp_ge_u32 s2, s1
	s_cselect_b32 s1, s5, s4
	s_xor_b32 s1, s1, s0
	s_sub_i32 s0, s1, s0
	v_mul_lo_u32 v187, s0, v5
	v_add_u32_e32 v4, s0, v187
	v_min_i32_e32 v185, 0x8800, v4
	v_mov_b32_e32 v251, 0x3ecc95a3
	v_mov_b32_e32 v239, 1
	v_mov_b32_e32 v183, 0xfc0
	v_mov_b32_e32 v182, 0x2000
	v_cmp_lt_i32_e32 vcc, v187, v185
	s_and_saveexec_b64 s[18:19], vcc
	s_cbranch_execz .LBB0_656
	s_load_dwordx2 s[0:1], s[80:81], 0x60
	s_add_u32 s20, s78, 0x8285000
	s_addc_u32 s21, s79, 0
	s_add_u32 s22, s78, 0x3e85000
	v_readlane_b32 s4, v255, 23
	s_addc_u32 s23, s79, 0
	s_mul_hi_i32 s2, s4, 0x6c00
	s_mulk_i32 s4, 0x6c00
	s_waitcnt lgkmcnt(0)
	s_add_u32 s0, s0, s4
	v_lshlrev_b32_e32 v4, 4, v186
	s_addc_u32 s1, s1, s2
	v_and_b32_e32 v180, 0x3f0, v4
	v_lshl_add_u64 v[76:77], s[0:1], 0, v[180:181]
	v_add_co_u32_e32 v20, vcc, s46, v76
	s_movk_i32 s2, 0x5000
	s_nop 0
	v_addc_co_u32_e32 v21, vcc, 0, v77, vcc
	v_add_co_u32_e32 v36, vcc, s2, v76
	s_movk_i32 s2, 0x4000
	s_nop 0
	v_addc_co_u32_e32 v37, vcc, 0, v77, vcc
	v_add_co_u32_e32 v52, vcc, s2, v76
	s_movk_i32 s2, 0x2000
	s_nop 0
	v_addc_co_u32_e32 v53, vcc, 0, v77, vcc
	v_add_co_u32_e32 v68, vcc, s84, v76
	v_mov_b32_e32 v114, v186
	s_nop 0
	v_addc_co_u32_e32 v69, vcc, 0, v77, vcc
	v_add_co_u32_e32 v84, vcc, s2, v76
	v_add_u32_e32 v112, 0xffffffbf, v187
	s_nop 0
	v_addc_co_u32_e32 v85, vcc, 0, v77, vcc
	v_add_co_u32_e32 v104, vcc, s83, v76
	v_mov_b32_e32 v143, 0x87ff
	s_nop 0
	v_addc_co_u32_e32 v105, vcc, 0, v77, vcc
	global_load_dwordx4 v[4:7], v[20:21], off offset:1024
	global_load_dwordx4 v[8:11], v[20:21], off
	global_load_dwordx4 v[12:15], v[36:37], off offset:2048
	global_load_dwordx4 v[16:19], v[36:37], off offset:1024
	s_nop 0
	global_load_dwordx4 v[20:23], v[20:21], off offset:2048
	s_nop 0
	global_load_dwordx4 v[24:27], v[36:37], off
	global_load_dwordx4 v[28:31], v[52:53], off offset:2048
	global_load_dwordx4 v[32:35], v[52:53], off offset:1024
	s_nop 0
	global_load_dwordx4 v[36:39], v[36:37], off offset:3072
	s_nop 0
	global_load_dwordx4 v[40:43], v[52:53], off
	global_load_dwordx4 v[44:47], v[68:69], off offset:2048
	global_load_dwordx4 v[48:51], v[68:69], off offset:1024
	s_nop 0
	global_load_dwordx4 v[52:55], v[52:53], off offset:3072
	s_nop 0
	global_load_dwordx4 v[56:59], v[68:69], off
	global_load_dwordx4 v[60:63], v[84:85], off offset:2048
	global_load_dwordx4 v[64:67], v[84:85], off offset:1024
	s_nop 0
	global_load_dwordx4 v[68:71], v[68:69], off offset:3072
	s_nop 0
	global_load_dwordx4 v[72:75], v[84:85], off
	global_load_dwordx4 v[76:79], v[104:105], off offset:2048
	global_load_dwordx4 v[80:83], v[104:105], off offset:1024
	s_nop 0
	global_load_dwordx4 v[84:87], v[84:85], off offset:3072
	s_nop 0
	global_load_dwordx4 v[88:91], v[104:105], off
	global_load_dwordx4 v[92:95], v180, s[0:1] offset:3072
	global_load_dwordx4 v[96:99], v180, s[0:1] offset:2048
	global_load_dwordx4 v[100:103], v180, s[0:1] offset:1024
	s_nop 0
	global_load_dwordx4 v[104:107], v[104:105], off offset:3072
	s_nop 0
	global_load_dwordx4 v[108:111], v180, s[0:1]
	v_med3_i32 v112, v112, 0, v143
	v_mul_u32_u24_e32 v180, 0xe00, v112
	v_lshlrev_b32_e32 v114, 3, v114
	v_lshl_add_u64 v[112:113], v[180:181], 1, s[20:21]
	v_and_b32_e32 v180, 0x1f8, v114
	v_lshl_add_u64 v[112:113], v[112:113], 0, v[180:181]
	s_mov_b64 s[4:5], 0x1200
	v_max_i32_e32 v116, 1, v187
	s_movk_i32 s0, 0xe00
	v_lshl_add_u64 v[114:115], v[112:113], 0, s[4:5]
	v_add_co_u32_e32 v112, vcc, s83, v112
	v_mul_lo_u32 v116, v116, s0
	v_mov_b32_e32 v117, v181
	v_addc_co_u32_e32 v113, vcc, 0, v113, vcc
	v_lshl_add_u64 v[116:117], v[116:117], 1, s[20:21]
	v_lshl_add_u64 v[116:117], v[116:117], 0, v[180:181]
	global_load_dwordx2 v[228:229], v[112:113], off offset:512
	global_load_dwordx2 v[222:223], v[114:115], off offset:512
	global_load_dwordx2 v[226:227], v[116:117], off offset:-2560
	global_load_dwordx2 v[198:199], v[114:115], off offset:1024
	v_max_i32_e32 v112, 0xffffffc1, v187
	v_add_u32_e32 v112, 63, v112
	v_min_u32_e32 v112, 0x87ff, v112
	v_mul_u32_u24_e32 v112, 0xe00, v112
	v_lshlrev_b32_e32 v112, 1, v112
	v_mov_b32_e32 v113, v181
	v_lshl_add_u64 v[112:113], s[20:21], 0, v[112:113]
	v_lshl_add_u64 v[112:113], v[112:113], 0, v[180:181]
	v_lshl_add_u64 v[114:115], v[112:113], 0, s[4:5]
	v_add_co_u32_e32 v112, vcc, s83, v112
	v_max_i32_e32 v124, 0xffffffbf, v187
	s_nop 0
	v_addc_co_u32_e32 v113, vcc, 0, v113, vcc
	global_load_dwordx2 v[224:225], v[112:113], off offset:512
	global_load_dwordx2 v[220:221], v[116:117], off offset:-2048
	global_load_dwordx2 v[196:197], v[116:117], off offset:-1536
	global_load_dwordx2 v[218:219], v[114:115], off offset:512
	global_load_dwordx2 v[194:195], v[114:115], off offset:1024
	v_mov_b32_e32 v114, v186
	v_subrev_u32_e32 v112, 64, v187
	v_med3_i32 v112, v112, 0, v143
	v_mul_u32_u24_e32 v180, 0xe00, v112
	v_lshlrev_b32_e32 v114, 3, v114
	v_lshl_add_u64 v[112:113], v[180:181], 1, s[20:21]
	v_and_b32_e32 v180, 0x1f8, v114
	v_max_i32_e32 v116, 0, v187
	v_lshl_add_u64 v[112:113], v[112:113], 0, v[180:181]
	v_mul_lo_u32 v116, v116, s0
	v_mov_b32_e32 v117, v181
	v_lshl_add_u64 v[114:115], v[112:113], 0, s[4:5]
	v_add_co_u32_e32 v112, vcc, s83, v112
	v_lshl_add_u64 v[116:117], v[116:117], 1, s[20:21]
	s_nop 0
	v_addc_co_u32_e32 v113, vcc, 0, v113, vcc
	v_lshl_add_u64 v[116:117], v[116:117], 0, v[180:181]
	v_lshl_add_u64 v[118:119], v[116:117], 0, s[4:5]
	global_load_dwordx2 v[192:193], v[112:113], off offset:512
	global_load_dwordx2 v[178:179], v[114:115], off offset:512
	global_load_dwordx2 v[176:177], v[118:119], off offset:512
	global_load_dwordx2 v[154:155], v[114:115], off offset:1024
	v_max_i32_e32 v114, 0xffffffc0, v187
	v_add_u32_e32 v114, 64, v114
	v_min_u32_e32 v114, 0x87ff, v114
	v_mul_u32_u24_e32 v114, 0xe00, v114
	v_lshlrev_b32_e32 v114, 1, v114
	v_mov_b32_e32 v115, v181
	v_add_co_u32_e32 v112, vcc, s83, v116
	v_lshl_add_u64 v[114:115], s[20:21], 0, v[114:115]
	s_nop 0
	v_addc_co_u32_e32 v113, vcc, 0, v117, vcc
	v_lshl_add_u64 v[114:115], v[114:115], 0, v[180:181]
	v_lshl_add_u64 v[116:117], v[114:115], 0, s[4:5]
	global_load_dwordx2 v[190:191], v[112:113], off offset:512
	global_load_dwordx2 v[174:175], v[116:117], off offset:512
	global_load_dwordx2 v[148:149], v[116:117], off offset:1024
	global_load_dwordx2 v[150:151], v[118:119], off offset:1024
	v_add_co_u32_e32 v112, vcc, s83, v114
	v_mov_b32_e32 v114, v186
	s_nop 0
	v_addc_co_u32_e32 v113, vcc, 0, v115, vcc
	global_load_dwordx2 v[188:189], v[112:113], off offset:512
	v_subrev_u32_e32 v112, 63, v187
	v_med3_i32 v112, v112, 0, v143
	v_mul_u32_u24_e32 v180, 0xe00, v112
	v_lshlrev_b32_e32 v114, 3, v114
	v_lshl_add_u64 v[112:113], v[180:181], 1, s[20:21]
	v_and_b32_e32 v180, 0x1f8, v114
	v_max_i32_e32 v114, -1, v187
	v_add_u32_e32 v114, 1, v114
	v_min_u32_e32 v114, 0x87ff, v114
	v_mul_u32_u24_e32 v114, 0xe00, v114
	v_add_u32_e32 v124, 0x41, v124
	v_lshl_add_u64 v[112:113], v[112:113], 0, v[180:181]
	v_lshlrev_b32_e32 v114, 1, v114
	v_mov_b32_e32 v115, v181
	v_min_u32_e32 v124, 0x87ff, v124
	v_lshl_add_u64 v[116:117], v[112:113], 0, s[4:5]
	v_add_co_u32_e32 v112, vcc, s83, v112
	v_lshl_add_u64 v[114:115], s[20:21], 0, v[114:115]
	v_mul_u32_u24_e32 v124, 0xe00, v124
	v_addc_co_u32_e32 v113, vcc, 0, v113, vcc
	v_lshl_add_u64 v[120:121], v[114:115], 0, v[180:181]
	v_lshlrev_b32_e32 v124, 1, v124
	v_mov_b32_e32 v125, v181
	v_lshl_add_u64 v[122:123], v[120:121], 0, s[4:5]
	v_add_co_u32_e32 v120, vcc, s83, v120
	v_lshl_add_u64 v[124:125], s[20:21], 0, v[124:125]
	s_nop 0
	v_addc_co_u32_e32 v121, vcc, 0, v121, vcc
	v_lshl_add_u64 v[126:127], v[124:125], 0, v[180:181]
	v_max_i32_e32 v130, 0xffffffbe, v187
	v_lshl_add_u64 v[128:129], v[126:127], 0, s[4:5]
	v_add_co_u32_e32 v126, vcc, s83, v126
	v_add_u32_e32 v130, 0x42, v130
	s_nop 0
	v_addc_co_u32_e32 v127, vcc, 0, v127, vcc
	v_mov_b32_e32 v132, v186
	v_min_u32_e32 v130, 0x87ff, v130
	global_load_dwordx2 v[112:113], v[112:113], off offset:512
	s_nop 0
	global_load_dwordx2 v[114:115], v[116:117], off offset:512
	global_load_dwordx2 v[118:119], v[122:123], off offset:512
	s_nop 0
	global_load_dwordx2 v[116:117], v[116:117], off offset:1024
	s_nop 0
	global_load_dwordx2 v[120:121], v[120:121], off offset:512
	s_nop 0
	global_load_dwordx2 v[124:125], v[128:129], off offset:512
	s_nop 0
	global_load_dwordx2 v[128:129], v[128:129], off offset:1024
	s_nop 0
	global_load_dwordx2 v[122:123], v[122:123], off offset:1024
	v_mul_u32_u24_e32 v130, 0xe00, v130
	global_load_dwordx2 v[126:127], v[126:127], off offset:512
	v_lshlrev_b32_e32 v180, 1, v130
	v_lshlrev_b32_e32 v132, 3, v132
	v_lshl_add_u64 v[130:131], s[20:21], 0, v[180:181]
	v_and_b32_e32 v180, 0x1f8, v132
	v_lshl_add_u64 v[130:131], v[130:131], 0, v[180:181]
	v_lshl_add_u64 v[136:137], v[130:131], 0, s[4:5]
	v_add_co_u32_e32 v132, vcc, s83, v130
	v_max_i32_e32 v130, -2, v187
	v_add_u32_e32 v130, 2, v130
	v_min_u32_e32 v130, 0x87ff, v130
	v_mul_u32_u24_e32 v130, 0xe00, v130
	v_addc_co_u32_e32 v133, vcc, 0, v131, vcc
	v_lshlrev_b32_e32 v130, 1, v130
	v_mov_b32_e32 v131, v181
	v_subrev_u32_e32 v142, 62, v187
	v_lshl_add_u64 v[130:131], s[20:21], 0, v[130:131]
	v_med3_i32 v142, v142, 0, v143
	v_lshl_add_u64 v[138:139], v[130:131], 0, v[180:181]
	v_mul_u32_u24_e32 v142, 0xe00, v142
	v_mov_b32_e32 v143, v181
	v_lshl_add_u64 v[140:141], v[138:139], 0, s[4:5]
	v_add_co_u32_e32 v138, vcc, s83, v138
	v_lshl_add_u64 v[142:143], v[142:143], 1, s[20:21]
	s_nop 0
	v_addc_co_u32_e32 v139, vcc, 0, v139, vcc
	v_lshl_add_u64 v[146:147], v[142:143], 0, v[180:181]
	global_load_dwordx2 v[130:131], v[136:137], off offset:1024
	global_load_dwordx2 v[134:135], v[132:133], off offset:512
	s_nop 0
	global_load_dwordx2 v[132:133], v[140:141], off offset:512
	s_nop 0
	global_load_dwordx2 v[136:137], v[136:137], off offset:512
	v_lshl_add_u64 v[152:153], v[146:147], 0, s[4:5]
	global_load_dwordx2 v[142:143], v[140:141], off offset:1024
	global_load_dwordx2 v[144:145], v[138:139], off offset:512
	s_nop 0
	global_load_dwordx2 v[138:139], v[152:153], off offset:1024
	global_load_dwordx2 v[140:141], v[152:153], off offset:512
	v_add_co_u32_e32 v146, vcc, s83, v146
	v_mov_b64_e32 v[152:153], s[78:79]
	s_nop 0
	v_addc_co_u32_e32 v147, vcc, 0, v147, vcc
	global_load_dwordx2 v[146:147], v[146:147], off offset:512
	s_movk_i32 s0, 0x600
	v_mad_i64_i32 v[152:153], s[0:1], v187, s0, v[152:153]
	s_mov_b64 s[0:1], 0x3e85400
	v_mov_b32_e32 v253, 0x87ff
	v_lshl_add_u64 v[152:153], v[152:153], 0, s[0:1]
	s_mov_b64 s[24:25], 0
	s_waitcnt vmcnt(0)
	s_branch .LBB0_627

.LBB0_626:
	s_or_b64 exec, exec, s[26:27]
	s_and_b64 s[0:1], exec, s[6:7]
	s_or_b64 s[24:25], s[0:1], s[24:25]
	s_mov_b64 s[0:1], 0xc00
	v_mov_b64_e32 v[198:199], v[154:155]
	v_mov_b64_e32 v[222:223], v[178:179]
	v_mov_b64_e32 v[228:229], v[192:193]
	v_lshl_add_u64 v[152:153], v[152:153], 0, s[0:1]
	v_mov_b64_e32 v[154:155], v[116:117]
	v_mov_b64_e32 v[178:179], v[114:115]
	v_mov_b64_e32 v[192:193], v[112:113]
	v_mov_b64_e32 v[226:227], v[190:191]
	v_mov_b64_e32 v[220:221], v[176:177]
	v_mov_b64_e32 v[196:197], v[150:151]
	v_mov_b64_e32 v[190:191], v[224:225]
	v_mov_b64_e32 v[176:177], v[218:219]
	v_mov_b64_e32 v[150:151], v[194:195]
	v_mov_b64_e32 v[224:225], v[188:189]
	v_mov_b64_e32 v[218:219], v[174:175]
	v_mov_b64_e32 v[194:195], v[148:149]
	v_mov_b64_e32 v[188:189], v[234:235]
	v_mov_b64_e32 v[174:175], v[232:233]
	v_mov_b64_e32 v[148:149], v[230:231]
	v_mov_b32_e32 v187, v243
	s_waitcnt vmcnt(21)
	v_mov_b64_e32 v[130:131], v[214:215]
	v_mov_b64_e32 v[136:137], v[210:211]
	s_waitcnt vmcnt(21)
	v_mov_b64_e32 v[134:135], v[216:217]
	v_mov_b64_e32 v[142:143], v[212:213]
	v_mov_b64_e32 v[132:133], v[206:207]
	v_mov_b64_e32 v[144:145], v[208:209]
	v_mov_b64_e32 v[146:147], v[200:201]
	v_mov_b64_e32 v[140:141], v[202:203]
	v_mov_b64_e32 v[138:139], v[204:205]
	v_mov_b32_e32 v112, v156
	v_mov_b32_e32 v113, v157
	v_mov_b32_e32 v114, v158
	v_mov_b32_e32 v115, v159
	v_mov_b32_e32 v116, v162
	v_mov_b32_e32 v117, v163
	v_mov_b32_e32 v120, v164
	v_mov_b32_e32 v121, v165
	v_mov_b32_e32 v118, v160
	v_mov_b32_e32 v119, v161
	v_mov_b32_e32 v122, v170
	v_mov_b32_e32 v123, v171
	v_mov_b32_e32 v126, v172
	v_mov_b32_e32 v127, v173
	v_mov_b32_e32 v124, v166
	v_mov_b32_e32 v125, v167
	v_mov_b32_e32 v128, v168
	v_mov_b32_e32 v129, v169
	s_andn2_b64 exec, exec, s[24:25]
	s_cbranch_execz .LBB0_656
.LBB0_627:
	v_add_u32_e32 v243, 2, v187
	v_mov_b32_e32 v204, v186
	v_cmp_lt_i32_e32 vcc, v243, v185
	v_cmp_ge_i32_e64 s[6:7], v243, v185
	s_waitcnt vmcnt(21)
	v_mov_b32_e32 v156, v112
	v_mov_b32_e32 v157, v113
	s_waitcnt vmcnt(21)
	v_mov_b32_e32 v158, v114
	v_mov_b32_e32 v159, v115
	s_waitcnt vmcnt(21)
	v_mov_b32_e32 v162, v116
	v_mov_b32_e32 v163, v117
	s_waitcnt vmcnt(21)
	v_mov_b32_e32 v164, v120
	v_mov_b32_e32 v165, v121
	v_mov_b32_e32 v160, v118
	v_mov_b32_e32 v161, v119
	s_waitcnt vmcnt(21)
	v_mov_b32_e32 v170, v122
	v_mov_b32_e32 v171, v123
	s_waitcnt vmcnt(21)
	v_mov_b32_e32 v172, v126
	v_mov_b32_e32 v173, v127
	v_mov_b32_e32 v166, v124
	v_mov_b32_e32 v167, v125
	v_mov_b32_e32 v168, v128
	v_mov_b32_e32 v169, v129
	s_and_saveexec_b64 s[8:9], vcc
	s_cbranch_execz .Lmx_skip629
	v_mov_b32_e32 v158, v186
	v_subrev_u32_e32 v156, 61, v187
	v_med3_i32 v156, v156, 0, v253
	v_mul_u32_u24_e32 v180, 0xe00, v156
	v_lshlrev_b32_e32 v158, 3, v158
	v_lshl_add_u64 v[156:157], v[180:181], 1, s[20:21]
	v_and_b32_e32 v180, 0x1f8, v158
	v_max_i32_e32 v158, -3, v187
	v_add_u32_e32 v158, 3, v158
	v_max_i32_e32 v166, 0xffffffbd, v187
	v_min_u32_e32 v158, 0x87ff, v158
	v_add_u32_e32 v166, 0x43, v166
	v_mul_u32_u24_e32 v158, 0xe00, v158
	v_min_u32_e32 v166, 0x87ff, v166
	v_lshl_add_u64 v[156:157], v[156:157], 0, v[180:181]
	s_mov_b64 s[0:1], 0x1200
	v_lshlrev_b32_e32 v158, 1, v158
	v_mov_b32_e32 v159, v181
	v_mul_u32_u24_e32 v166, 0xe00, v166
	v_lshl_add_u64 v[162:163], v[156:157], 0, s[0:1]
	v_add_co_u32_e32 v156, vcc, 0x1000, v156
	v_lshl_add_u64 v[158:159], s[20:21], 0, v[158:159]
	v_lshlrev_b32_e32 v166, 1, v166
	v_mov_b32_e32 v167, v181
	v_addc_co_u32_e32 v157, vcc, 0, v157, vcc
	v_lshl_add_u64 v[164:165], v[158:159], 0, v[180:181]
	v_lshl_add_u64 v[166:167], s[20:21], 0, v[166:167]
	v_lshl_add_u64 v[170:171], v[164:165], 0, s[0:1]
	v_add_co_u32_e32 v164, vcc, s83, v164
	v_lshl_add_u64 v[172:173], v[166:167], 0, v[180:181]
	s_nop 0
	v_addc_co_u32_e32 v165, vcc, 0, v165, vcc
	v_lshl_add_u64 v[168:169], v[172:173], 0, s[0:1]
	global_load_dwordx2 v[156:157], v[156:157], off offset:512
	s_nop 0
	global_load_dwordx2 v[158:159], v[162:163], off offset:512
	global_load_dwordx2 v[160:161], v[170:171], off offset:512
	s_nop 0
	global_load_dwordx2 v[162:163], v[162:163], off offset:1024
	s_nop 0
	global_load_dwordx2 v[164:165], v[164:165], off offset:512
	s_nop 0
	global_load_dwordx2 v[166:167], v[168:169], off offset:512
	s_nop 0
	global_load_dwordx2 v[168:169], v[168:169], off offset:1024
	s_nop 0
	global_load_dwordx2 v[170:171], v[170:171], off offset:1024
	v_add_co_u32_e32 v172, vcc, s83, v172
	s_nop 1
	v_addc_co_u32_e32 v173, vcc, 0, v173, vcc
	global_load_dwordx2 v[172:173], v[172:173], off offset:512

.LBB0_641:
	s_or_b64 exec, exec, s[8:9]
	v_lshlrev_b32_e32 v194, 16, v212
	v_and_b32_e32 v195, 0xffff0000, v212
	v_pk_fma_f32 v[194:195], v[22:23], v[194:195], v[204:205]
	v_and_b32_e32 v199, 0xffff0000, v180
	v_mul_f32_e32 v196, 0xbfb8aa3b, v195
	v_exp_f32_e32 v196, v196
	v_mul_f32_e32 v197, 0xbfb8aa3b, v194
	v_exp_f32_e32 v198, v197
	v_add_u32_e32 v223, 1, v187
	v_add_f32_e32 v196, 1.0, v196
	v_rcp_f32_e32 v197, v196
	v_add_f32_e32 v196, 1.0, v198
	v_lshlrev_b32_e32 v198, 16, v180
	v_pk_fma_f32 v[198:199], v[20:21], v[198:199], v[202:203]
	v_rcp_f32_e32 v196, v196
	v_mul_f32_e32 v180, 0xbfb8aa3b, v199
	v_exp_f32_e32 v180, v180
	v_mul_f32_e32 v202, 0xbfb8aa3b, v198
	v_exp_f32_e32 v202, v202
	v_pk_mul_f32 v[194:195], v[194:195], v[196:197]
	v_add_f32_e32 v180, 1.0, v180
	v_rcp_f32_e32 v203, v180
	v_add_f32_e32 v180, 1.0, v202
	v_rcp_f32_e32 v202, v180
	v_cmp_lt_i32_e32 vcc, v223, v185
	s_waitcnt vmcnt(32)
	v_mov_b64_e32 v[214:215], v[130:131]
	s_waitcnt vmcnt(32)
	v_mov_b64_e32 v[210:211], v[136:137]
	v_pk_mul_f32 v[196:197], v[198:199], v[202:203]
	v_mov_b64_e32 v[216:217], v[134:135]
	v_cvt_pk_bf16_f32 v196, v196, v197
	v_cvt_pk_bf16_f32 v197, v194, v195
	global_store_dwordx2 v[200:201], v[196:197], off
	s_waitcnt vmcnt(33)
	v_mov_b64_e32 v[212:213], v[142:143]
	v_mov_b64_e32 v[206:207], v[132:133]
	s_waitcnt vmcnt(33)
	v_mov_b64_e32 v[208:209], v[144:145]
	s_waitcnt vmcnt(33)
	v_mov_b64_e32 v[200:201], v[146:147]
	v_mov_b64_e32 v[202:203], v[140:141]
	v_mov_b64_e32 v[204:205], v[138:139]
	v_mov_b64_e32 v[230:231], v[128:129]
	v_mov_b64_e32 v[232:233], v[124:125]
	v_mov_b64_e32 v[234:235], v[126:127]
	v_mov_b64_e32 v[194:195], v[122:123]
	v_mov_b64_e32 v[218:219], v[118:119]
	v_mov_b64_e32 v[224:225], v[120:121]
	s_and_saveexec_b64 s[26:27], vcc
	s_cbranch_execz .Lmx_skip626
	v_add_u32_e32 v180, 3, v187
	v_mov_b32_e32 v224, v186
	v_cmp_lt_i32_e32 vcc, v180, v185
	v_mov_b64_e32 v[204:205], v[138:139]
	v_mov_b64_e32 v[202:203], v[140:141]
	v_mov_b64_e32 v[200:201], v[146:147]
	v_mov_b64_e32 v[208:209], v[144:145]
	v_mov_b64_e32 v[206:207], v[132:133]
	v_mov_b64_e32 v[212:213], v[142:143]
	v_mov_b64_e32 v[216:217], v[134:135]
	v_mov_b64_e32 v[210:211], v[136:137]
	v_mov_b64_e32 v[214:215], v[130:131]
	s_and_saveexec_b64 s[8:9], vcc
	s_cbranch_execz .Lmx_skip644
	v_subrev_u32_e32 v180, 60, v187
	v_med3_i32 v180, v180, 0, v253
	v_max_i32_e32 v198, -3, v223
	v_mov_b32_e32 v196, v186
	v_mul_u32_u24_e32 v180, 0xe00, v180
	v_add_u32_e32 v198, 3, v198
	v_lshl_add_u64 v[194:195], v[180:181], 1, s[20:21]
	v_lshlrev_b32_e32 v180, 3, v196
	v_min_u32_e32 v198, 0x87ff, v198
	v_and_b32_e32 v180, 0x1f8, v180
	v_mul_u32_u24_e32 v198, 0xe00, v198
	v_lshl_add_u64 v[194:195], v[194:195], 0, v[180:181]
	s_mov_b64 s[0:1], 0x1200
	v_lshlrev_b32_e32 v198, 1, v198
	v_mov_b32_e32 v199, v181
	v_lshl_add_u64 v[196:197], v[194:195], 0, s[0:1]
	v_add_co_u32_e32 v194, vcc, 0x1000, v194
	v_lshl_add_u64 v[198:199], s[20:21], 0, v[198:199]
	s_nop 0
	v_addc_co_u32_e32 v195, vcc, 0, v195, vcc
	v_lshl_add_u64 v[198:199], v[198:199], 0, v[180:181]
	v_lshl_add_u64 v[212:213], v[198:199], 0, s[0:1]
	global_load_dwordx2 v[200:201], v[194:195], off offset:512
	global_load_dwordx2 v[202:203], v[196:197], off offset:512
	global_load_dwordx2 v[206:207], v[212:213], off offset:512
	global_load_dwordx2 v[204:205], v[196:197], off offset:1024
	v_max_i32_e32 v196, 0xffffffbc, v187
	v_add_u32_e32 v196, 0x44, v196
	v_min_u32_e32 v196, 0x87ff, v196
	v_mul_u32_u24_e32 v196, 0xe00, v196
	v_lshlrev_b32_e32 v196, 1, v196
	v_mov_b32_e32 v197, v181
	v_add_co_u32_e32 v194, vcc, s83, v198
	v_lshl_add_u64 v[196:197], s[20:21], 0, v[196:197]
	s_nop 0
	v_addc_co_u32_e32 v195, vcc, 0, v199, vcc
	v_lshl_add_u64 v[196:197], v[196:197], 0, v[180:181]
	v_lshl_add_u64 v[198:199], v[196:197], 0, s[0:1]
	global_load_dwordx2 v[208:209], v[194:195], off offset:512
	global_load_dwordx2 v[210:211], v[198:199], off offset:512
	global_load_dwordx2 v[214:215], v[198:199], off offset:1024
	s_nop 0
	global_load_dwordx2 v[212:213], v[212:213], off offset:1024
	v_add_co_u32_e32 v194, vcc, 0x1000, v196
	s_nop 1
	v_addc_co_u32_e32 v195, vcc, 0, v197, vcc
	global_load_dwordx2 v[216:217], v[194:195], off offset:512
	v_add_u32_e32 v0, 5, v187
	v_mul_u32_u24_e32 v0, 0xe00, v0
	v_lshlrev_b32_e32 v0, 1, v0
	v_add_u32_e32 v0, v0, v180
	v_add_u32_e32 v0, 0x1000, v0
	v_mov_b32_e32 v1, 0
	v_lshl_add_u64 v[0:1], s[20:21], 0, v[0:1]
	global_load_dword v2, v[0:1], off offset:512
	global_load_dword v2, v[0:1], off offset:1024
	global_load_dword v2, v[0:1], off offset:1536
	v_add_co_u32_e32 v0, vcc, 0x1c00, v0
	v_addc_co_u32_e32 v1, vcc, 0, v1, vcc
	global_load_dword v2, v[0:1], off offset:512
	global_load_dword v2, v[0:1], off offset:1024
	global_load_dword v2, v[0:1], off offset:1536
	v_add_co_u32_e32 v0, vcc, 0x6e400, v0
	v_addc_co_u32_e32 v1, vcc, 0, v1, vcc
	global_load_dword v2, v[0:1], off offset:512
	global_load_dword v2, v[0:1], off offset:1024
	global_load_dword v2, v[0:1], off offset:1536
	v_add_co_u32_e32 v0, vcc, 0x1c00, v0
	v_addc_co_u32_e32 v1, vcc, 0, v1, vcc
	global_load_dword v2, v[0:1], off offset:512
	global_load_dword v2, v[0:1], off offset:1024
	global_load_dword v2, v[0:1], off offset:1536
	v_subrev_co_u32_e32 v0, vcc, 0xe1c00, v0
	v_subbrev_co_u32_e32 v1, vcc, 0, v1, vcc
	global_load_dword v2, v[0:1], off offset:512
	global_load_dword v2, v[0:1], off offset:1024
	global_load_dword v2, v[0:1], off offset:1536
	v_add_co_u32_e32 v0, vcc, 0x1c00, v0
	v_addc_co_u32_e32 v1, vcc, 0, v1, vcc
	global_load_dword v2, v[0:1], off offset:512
	global_load_dword v2, v[0:1], off offset:1024
	global_load_dword v2, v[0:1], off offset:1536

.LBB0_654:
	s_andn2_saveexec_b64 s[8:9], s[28:29]
	s_cbranch_execz .LBB0_625
	v_lshlrev_b32_e32 v174, 16, v154
	v_and_b32_e32 v175, 0xffff0000, v154
	v_pk_fma_f32 v[174:175], v[96:97], v[174:175], 0 op_sel_hi:[1,1,0]
	v_lshlrev_b32_e32 v176, 16, v116
	v_and_b32_e32 v177, 0xffff0000, v116
	v_pk_fma_f32 v[174:175], v[80:81], v[176:177], v[174:175]
	v_lshlrev_b32_e32 v176, 16, v138
	v_and_b32_e32 v177, 0xffff0000, v138
	v_pk_fma_f32 v[174:175], v[72:73], v[176:177], v[174:175]
	v_lshlrev_b32_e32 v176, 16, v150
	v_and_b32_e32 v177, 0xffff0000, v150
	v_pk_fma_f32 v[174:175], v[84:85], v[176:177], v[174:175]
	v_lshlrev_b32_e32 v176, 16, v122
	v_and_b32_e32 v177, 0xffff0000, v122
	v_pk_fma_f32 v[174:175], v[44:45], v[176:177], v[174:175]
	v_lshlrev_b32_e32 v176, 16, v142
	v_and_b32_e32 v177, 0xffff0000, v142
	v_pk_fma_f32 v[174:175], v[32:33], v[176:177], v[174:175]
	v_lshlrev_b32_e32 v176, 16, v148
	v_and_b32_e32 v177, 0xffff0000, v148
	v_lshlrev_b32_e32 v154, 16, v155
	v_and_b32_e32 v155, 0xffff0000, v155
	v_pk_fma_f32 v[174:175], v[24:25], v[176:177], v[174:175]
	v_lshlrev_b32_e32 v176, 16, v128
	v_and_b32_e32 v177, 0xffff0000, v128
	v_pk_fma_f32 v[174:175], v[36:37], v[176:177], v[174:175]
	v_pk_fma_f32 v[154:155], v[98:99], v[154:155], 0 op_sel_hi:[1,1,0]
	v_lshlrev_b32_e32 v176, 16, v117
	v_and_b32_e32 v177, 0xffff0000, v117
	v_pk_fma_f32 v[154:155], v[82:83], v[176:177], v[154:155]
	v_lshlrev_b32_e32 v176, 16, v139
	v_and_b32_e32 v177, 0xffff0000, v139
	v_pk_fma_f32 v[154:155], v[74:75], v[176:177], v[154:155]
	v_lshlrev_b32_e32 v150, 16, v151
	v_and_b32_e32 v151, 0xffff0000, v151
	v_pk_fma_f32 v[150:151], v[86:87], v[150:151], v[154:155]
	v_lshlrev_b32_e32 v154, 16, v123
	v_and_b32_e32 v155, 0xffff0000, v123
	v_pk_fma_f32 v[150:151], v[46:47], v[154:155], v[150:151]
	v_lshlrev_b32_e32 v154, 16, v143
	v_and_b32_e32 v155, 0xffff0000, v143
	v_pk_fma_f32 v[150:151], v[34:35], v[154:155], v[150:151]
	v_lshlrev_b32_e32 v148, 16, v149
	v_and_b32_e32 v149, 0xffff0000, v149
	v_pk_fma_f32 v[148:149], v[26:27], v[148:149], v[150:151]
	v_lshlrev_b32_e32 v150, 16, v129
	v_and_b32_e32 v151, 0xffff0000, v129
	v_pk_fma_f32 v[178:179], v[38:39], v[150:151], v[148:149]
	v_mov_b64_e32 v[176:177], v[130:131]
	s_branch .LBB0_625
.Lmx_skip629:
	s_waitcnt vmcnt(0)
	s_branch .LBB0_629

.LBB0_656:
	s_or_b64 exec, exec, s[18:19]
	s_waitcnt vmcnt(0)
	v_mov_b32_e32 v0, v181
	v_mov_b32_e32 v1, v181
	v_mov_b32_e32 v2, v181
	v_mov_b32_e32 v3, v181
	v_mov_b32_e32 v232, v182
	v_mov_b32_e32 v182, v183
